# mixer B: bias/window-mask block rewritten (window mask folded into the LDS bias table as -inf, 16 bias reads issued together, one wait)
# baseline (speedup 1.0000x reference)
.LBB0_2756:
	s_mov_b32 s30, 0x66666667
	v_mul_hi_i32 v58, v57, s30
	v_lshrrev_b32_e32 v59, 31, v58
	v_ashrrev_i32_e32 v58, 7, v58
	v_add_u32_e32 v58, v58, v59
	s_movk_i32 s30, 0xfec0
	v_mad_i32_i24 v60, v58, s30, v57
	v_add_u32_e32 v59, 0xffffffa0, v60
	v_cmp_gt_u32_e32 vcc, s63, v59
	v_mov_b32_e32 v59, v224
	s_and_saveexec_b64 s[30:31], vcc
	s_cbranch_execz .LBB0_2755
	v_mul_i32_i24_e32 v59, 0xfffffec0, v58
	s_movk_i32 s34, 0xd0
	v_sub_u32_e32 v59, v54, v59
	v_cmp_gt_u32_e32 vcc, s34, v60
	s_and_saveexec_b64 s[34:35], vcc
	s_cbranch_execz .LBB0_2754
	v_cvt_f32_u32_e32 v59, v59
	s_mov_b32 s49, 0x800000
	v_mul_f32_e32 v59, 0x3d800000, v59
	v_cmp_gt_f32_e32 vcc, s49, v59
	s_mov_b32 s49, 0x3f317217
	s_nop 0
	v_cndmask_b32_e64 v60, 0, 32, vcc
	v_ldexp_f32 v59, v59, v60
	v_log_f32_e32 v59, v59
	v_cndmask_b32_e32 v60, 0, v220, vcc
	v_mul_f32_e32 v61, 0x3f317217, v59
	v_fma_f32 v61, v59, s49, -v61
	v_fmac_f32_e32 v61, 0x3377d1cf, v59
	s_mov_b32 s49, 0x7f800000
	v_fmac_f32_e32 v61, 0x3f317217, v59
	v_cmp_lt_f32_e64 vcc, |v59|, s49
	s_mov_b32 s49, 0x40051592
	s_nop 0
	v_cndmask_b32_e32 v59, v59, v61, vcc
	v_sub_f32_e32 v59, v59, v60
	v_div_scale_f32 v60, s[52:53], s49, s49, v59
	v_rcp_f32_e32 v61, v60
	v_div_scale_f32 v62, vcc, v59, s49, v59
	v_fma_f32 v63, -v60, v61, 1.0
	v_fmac_f32_e32 v61, v63, v61
	v_mul_f32_e32 v63, v62, v61
	v_fma_f32 v64, -v60, v63, v62
	v_fmac_f32_e32 v63, v64, v61
	v_fma_f32 v60, -v60, v63, v62
	v_div_fmas_f32 v60, v60, v61, v63
	v_div_fixup_f32 v59, v60, s49, v59
	v_mul_f32_e32 v59, 0x41800000, v59
	v_cvt_i32_f32_e32 v59, v59
	v_min_i32_e32 v59, 15, v59
	v_add_u32_e32 v59, 16, v59
	s_branch .LBB0_2754

.LBB0_2773:
	s_cmp_gt_i32 s18, s21
	s_cselect_b64 s[16:17], -1, 0
	s_add_i32 s19, s18, 63
	s_cmp_lt_i32 s19, s22
	s_cselect_b64 s[26:27], -1, 0
	s_or_b64 s[16:17], s[16:17], s[26:27]
	s_and_b64 vcc, exec, s[16:17]
	s_cbranch_vccnz .LBB0_2779
	v_add_u32_e32 v132, 0, v120
	ds_read_b128 v[52:55], v132 offset:4608
	ds_read_b128 v[36:39], v132
	ds_read_b128 v[124:127], v132 offset:32
	ds_read_b128 v[128:131], v132 offset:4640
	s_waitcnt lgkmcnt(3)
	v_mfma_f32_32x32x16_bf16 v[52:67], v[52:55], v[84:87], 0
	s_waitcnt lgkmcnt(2)
	v_mfma_f32_32x32x16_bf16 v[36:51], v[36:39], v[84:87], 0
	s_waitcnt lgkmcnt(1)
	v_mfma_f32_32x32x16_bf16 v[36:51], v[124:127], v[88:91], v[36:51]
	s_waitcnt lgkmcnt(0)
	v_mfma_f32_32x32x16_bf16 v[52:67], v[128:131], v[88:91], v[52:67]
	ds_read_b128 v[124:127], v132 offset:64
	ds_read_b128 v[128:131], v132 offset:4672
	s_waitcnt lgkmcnt(1)
	v_mfma_f32_32x32x16_bf16 v[36:51], v[124:127], v[92:95], v[36:51]
	s_waitcnt lgkmcnt(0)
	v_mfma_f32_32x32x16_bf16 v[52:67], v[128:131], v[92:95], v[52:67]
	ds_read_b128 v[124:127], v132 offset:96
	ds_read_b128 v[128:131], v132 offset:4704
	s_waitcnt lgkmcnt(1)
	v_mfma_f32_32x32x16_bf16 v[36:51], v[124:127], v[96:99], v[36:51]
	s_waitcnt lgkmcnt(0)
	v_mfma_f32_32x32x16_bf16 v[52:67], v[128:131], v[96:99], v[52:67]
	v_add_u32_e32 v144, 0x19b7c, v119
	ds_read2_b32 v[146:147], v144 offset0:0 offset1:1
	ds_read2_b32 v[148:149], v144 offset0:2 offset1:3
	ds_read2_b32 v[150:151], v144 offset0:8 offset1:9
	ds_read2_b32 v[152:153], v144 offset0:10 offset1:11
	ds_read2_b32 v[154:155], v144 offset0:16 offset1:17
	ds_read2_b32 v[156:157], v144 offset0:18 offset1:19
	ds_read2_b32 v[158:159], v144 offset0:24 offset1:25
	ds_read2_b32 v[160:161], v144 offset0:26 offset1:27
	ds_read2_b32 v[162:163], v144 offset0:32 offset1:33
	ds_read2_b32 v[164:165], v144 offset0:34 offset1:35
	ds_read2_b32 v[166:167], v144 offset0:40 offset1:41
	ds_read2_b32 v[168:169], v144 offset0:42 offset1:43
	ds_read2_b32 v[170:171], v144 offset0:48 offset1:49
	ds_read2_b32 v[172:173], v144 offset0:50 offset1:51
	ds_read2_b32 v[174:175], v144 offset0:56 offset1:57
	ds_read2_b32 v[176:177], v144 offset0:58 offset1:59
	s_waitcnt lgkmcnt(0)
	v_add_f32_e32 v124, v36, v146
	v_add_f32_e32 v128, v42, v152
	v_add_f32_e32 v129, v43, v153
	v_add_f32_e32 v126, v44, v154
	v_add_f32_e32 v127, v45, v155
	v_add_f32_e32 v36, v52, v162
	v_add_f32_e32 v52, v54, v164
	v_add_f32_e32 v42, v58, v168
	v_add_f32_e32 v43, v59, v169
	v_add_f32_e32 v44, v60, v170
	v_add_f32_e32 v45, v61, v171
	v_add_f32_e32 v130, v62, v172
	v_add_f32_e32 v131, v63, v173
	v_add_f32_e32 v132, v64, v174
	v_add_f32_e32 v133, v65, v175
	v_add_f32_e32 v125, v66, v176
	v_add_f32_e32 v134, v67, v177
	v_add_f32_e32 v54, v38, v148
	v_add_f32_e32 v60, v46, v156
	v_add_f32_e32 v61, v47, v157
	v_add_f32_e32 v62, v48, v158
	v_add_f32_e32 v63, v49, v159
	v_add_f32_e32 v64, v50, v160
	v_add_f32_e32 v65, v51, v161
	v_add_f32_e32 v180, v37, v147
	v_add_f32_e32 v37, v53, v163
	v_add_f32_e32 v181, v39, v149
	v_add_f32_e32 v39, v55, v165
	v_add_f32_e32 v182, v40, v150
	v_add_f32_e32 v40, v56, v166
	v_add_f32_e32 v183, v41, v151
	v_add_f32_e32 v41, v57, v167
	v_mov_b32_e32 v53, v180
	v_mov_b32_e32 v55, v181
	v_mov_b32_e32 v56, v182
	v_mov_b32_e32 v57, v183
	v_max_f32_e32 v38, v124, v53
	v_max3_f32 v38, v38, v54, v55
	v_max3_f32 v38, v38, v56, v57
	v_max3_f32 v38, v38, v128, v129
	v_max3_f32 v38, v38, v126, v127
	v_max3_f32 v38, v38, v60, v61
	v_max3_f32 v38, v38, v62, v63
	v_max3_f32 v38, v38, v64, v65
	v_max3_f32 v38, v38, v36, v37
	v_max3_f32 v38, v38, v52, v39
	v_max3_f32 v38, v38, v40, v41
	v_max3_f32 v38, v38, v42, v43
	v_max3_f32 v38, v38, v44, v45
	v_max3_f32 v38, v38, v130, v131
	v_max3_f32 v38, v38, v132, v133
	v_max3_f32 v38, v38, v125, v134
	v_mov_b32_e32 v46, v38
	s_nop 1
	v_permlane32_swap_b32_e32 v38, v46
	v_max3_f32 v38, v123, v38, v46
	v_sub_f32_e32 v46, v124, v38
	v_exp_f32_e32 v46, v46
	v_sub_f32_e32 v47, v53, v38
	v_exp_f32_e32 v47, v47
	v_sub_f32_e32 v36, v36, v38
	v_add_f32_e32 v48, 0, v46
	v_exp_f32_e32 v36, v36
	v_add_f32_e32 v49, v47, v48
	v_sub_f32_e32 v48, v54, v38
	v_exp_f32_e32 v48, v48
	v_sub_f32_e32 v37, v37, v38
	v_exp_f32_e32 v37, v37
	v_sub_f32_e32 v52, v52, v38
	v_add_f32_e32 v50, v48, v49
	v_sub_f32_e32 v49, v55, v38
	v_exp_f32_e32 v49, v49
	v_exp_f32_e32 v52, v52
	v_sub_f32_e32 v39, v39, v38
	v_exp_f32_e32 v39, v39
	v_add_f32_e32 v51, v49, v50
	v_sub_f32_e32 v50, v56, v38
	v_exp_f32_e32 v50, v50
	v_sub_f32_e32 v40, v40, v38
	v_exp_f32_e32 v40, v40
	v_sub_f32_e32 v41, v41, v38
	v_add_f32_e32 v53, v50, v51
	v_sub_f32_e32 v51, v57, v38
	v_exp_f32_e32 v51, v51
	v_exp_f32_e32 v41, v41
	v_sub_f32_e32 v42, v42, v38
	v_exp_f32_e32 v42, v42
	v_add_f32_e32 v54, v51, v53
	v_sub_f32_e32 v53, v128, v38
	v_exp_f32_e32 v53, v53
	v_sub_f32_e32 v43, v43, v38
	v_exp_f32_e32 v43, v43
	v_sub_f32_e32 v44, v44, v38
	v_add_f32_e32 v55, v53, v54
	v_sub_f32_e32 v54, v129, v38
	v_exp_f32_e32 v54, v54
	v_exp_f32_e32 v44, v44
	v_sub_f32_e32 v45, v45, v38
	v_exp_f32_e32 v45, v45
	v_add_f32_e32 v56, v54, v55
	v_sub_f32_e32 v55, v126, v38
	v_exp_f32_e32 v55, v55
	v_sub_f32_e32 v135, v123, v38
	v_add_f32_e32 v57, v55, v56
	v_sub_f32_e32 v56, v127, v38
	v_exp_f32_e32 v56, v56
	s_nop 0
	v_add_f32_e32 v58, v56, v57
	v_sub_f32_e32 v57, v60, v38
	v_exp_f32_e32 v57, v57
	s_nop 0
	v_add_f32_e32 v59, v57, v58
	v_sub_f32_e32 v58, v61, v38
	v_exp_f32_e32 v58, v58
	s_nop 0
	v_add_f32_e32 v60, v58, v59
	v_sub_f32_e32 v59, v62, v38
	v_exp_f32_e32 v59, v59
	s_nop 0
	v_add_f32_e32 v61, v59, v60
	v_sub_f32_e32 v60, v63, v38
	v_exp_f32_e32 v60, v60
	s_nop 0
	v_add_f32_e32 v62, v60, v61
	v_sub_f32_e32 v61, v64, v38
	v_exp_f32_e32 v61, v61
	s_nop 0
	v_add_f32_e32 v63, v61, v62
	v_sub_f32_e32 v62, v65, v38
	v_exp_f32_e32 v62, v62
	s_nop 0
	v_add_f32_e32 v63, v62, v63
	v_add_f32_e32 v63, v36, v63
	v_add_f32_e32 v63, v37, v63
	v_add_f32_e32 v63, v52, v63
	v_add_f32_e32 v63, v39, v63
	v_add_f32_e32 v63, v40, v63
	v_add_f32_e32 v63, v41, v63
	v_add_f32_e32 v63, v42, v63
	v_add_f32_e32 v63, v43, v63
	v_add_f32_e32 v63, v44, v63
	v_add_f32_e32 v64, v45, v63
	v_sub_f32_e32 v63, v130, v38
	v_exp_f32_e32 v63, v63
	s_nop 0
	v_add_f32_e32 v65, v63, v64
	v_sub_f32_e32 v64, v131, v38
	v_exp_f32_e32 v64, v64
	s_nop 0
	v_add_f32_e32 v66, v64, v65
	v_sub_f32_e32 v65, v132, v38
	v_exp_f32_e32 v65, v65
	s_nop 0
	v_add_f32_e32 v67, v65, v66
	v_sub_f32_e32 v66, v133, v38
	v_exp_f32_e32 v66, v66
	s_nop 0
	v_add_f32_e32 v123, v66, v67
	v_sub_f32_e32 v67, v125, v38
	v_exp_f32_e32 v67, v67
	s_nop 0
	v_add_f32_e32 v124, v67, v123
	v_sub_f32_e32 v123, v134, v38
	v_exp_f32_e32 v123, v123
	s_nop 0
	v_add_f32_e32 v125, v123, v124
	v_exp_f32_e32 v124, v135
	v_mov_b32_e32 v126, v125
	s_nop 1
	v_permlane32_swap_b32_e32 v125, v126
	v_cmp_gt_f32_e32 vcc, 1.0, v124
	s_cbranch_vccz .LBB0_2778
	s_and_saveexec_b64 s[16:17], s[4:5]
	ds_write_b32 v110, v124 offset:128
	s_or_b64 exec, exec, s[16:17]
	s_waitcnt lgkmcnt(0)
	ds_read_b128 v[128:131], v111 offset:224
	ds_read_b128 v[132:135], v111 offset:192
	ds_read_b128 v[136:139], v111 offset:160
	ds_read_b128 v[140:143], v111 offset:128
	s_waitcnt lgkmcnt(3)
	v_pk_mul_f32 v[18:19], v[18:19], v[130:131]
	s_waitcnt lgkmcnt(2)
	v_pk_mul_f32 v[14:15], v[14:15], v[134:135]
	s_waitcnt lgkmcnt(1)
	v_pk_mul_f32 v[10:11], v[10:11], v[138:139]
	s_waitcnt lgkmcnt(0)
	v_pk_mul_f32 v[6:7], v[6:7], v[142:143]
	v_pk_mul_f32 v[34:35], v[34:35], v[130:131]
	v_pk_mul_f32 v[30:31], v[30:31], v[134:135]
	v_pk_mul_f32 v[26:27], v[26:27], v[138:139]
	v_pk_mul_f32 v[22:23], v[22:23], v[142:143]
	v_pk_mul_f32 v[16:17], v[16:17], v[128:129]
	v_pk_mul_f32 v[12:13], v[12:13], v[132:133]
	v_pk_mul_f32 v[8:9], v[8:9], v[136:137]
	v_pk_mul_f32 v[4:5], v[4:5], v[140:141]
	v_pk_mul_f32 v[32:33], v[32:33], v[128:129]
	v_pk_mul_f32 v[28:29], v[28:29], v[132:133]
	v_pk_mul_f32 v[24:25], v[24:25], v[136:137]
	v_pk_mul_f32 v[20:21], v[20:21], v[140:141]
